# cross-attention LDS loop software-pipelined: next tile's QK MFMAs issued between this tile's softmax VALU (two score accumulators)
# baseline (speedup 1.0000x reference)
; __device__ __forceinline__ void xattn_phase(const bf16* QXB, const bf16* MKF, const bf16* MVF, bf16* OXB, int G, int tid) {
;     ...
;     for (int it = (int)blockIdx.x * (MK_THREADS / 64) + wave; it < NIT; it += G * (MK_THREADS / 64)) { const int qb = it % NQ32, bhx = it / NQ32, h = bhx % XH, b = bhx / XH;
;         const size_t row0 = (size_t)b * SEQ + 32 * qb;
;         const bf16* qp = QXB + (row0 + r32) * XW + h * XHD + 8 * hh; const bf16* kp = MKF + (size_t)(b * XH + h) * 32768 + lane * 8;
;         bf16x8 qf[8];
; #pragma unroll
;         for (int ks = 0; ks < 8; ++ks) qf[ks] = *(const bf16x8*)(qp + 16 * ks);
;         const bf16* vp = MVF + (size_t)(b * XH + h) * 32768 + lane * 16;
;         f32x16 o[4]; o[0] = f32x16{}; o[1] = f32x16{}; o[2] = f32x16{}; o[3] = f32x16{}; float m_run = -INFINITY, l_run = 0.f;
;     ...
;         bf16x8 kfa[8], kfb[8];
; #pragma unroll
;         for (int ks = 0; ks < 8; ++ks) kfa[ks] = *(const bf16x8*)(kp + ks * 512);
.LBB0_1511:
	s_ashr_i32 s0, s8, 31
	s_lshr_b32 s1, s0, 25
	s_add_i32 s1, s8, s1
	s_ashr_i32 s2, s1, 7
	s_and_b32 s1, s1, 0x7ffff80
	s_sub_i32 s6, s8, s1
	s_lshr_b32 s1, s2, 30
	s_add_i32 s1, s2, s1
	s_lshr_b32 s0, s0, 23
	s_and_b32 s1, s1, -4
	s_add_i32 s0, s8, s0
	s_sub_i32 s7, s2, s1
	s_ashr_i32 s2, s0, 9
	s_ashr_i32 s3, s2, 31
	s_lshl_b64 s[0:1], s[2:3], 12
	s_lshl_b32 s3, s6, 5
	s_ashr_i32 s6, s3, 31
	s_add_u32 s0, s0, s3
	s_addc_u32 s1, s1, s6
	v_mov_b32_e32 v3, s1
	v_or_b32_e32 v2, s0, v222
	v_readlane_b32 s0, v252, 19
	v_lshlrev_b64 v[4:5], 10, v[2:3]
	v_readlane_b32 s1, v252, 20
	s_lshl_b32 s2, s2, 2
	s_add_i32 s2, s2, s7
	v_lshl_add_u64 v[4:5], s[0:1], 0, v[4:5]
	s_lshl_b32 s0, s7, 7
	s_ashr_i32 s1, s0, 31
	v_lshl_add_u64 v[4:5], s[0:1], 1, v[4:5]
	v_lshl_add_u64 v[4:5], v[4:5], 0, v[214:215]
	s_ashr_i32 s3, s2, 31
	global_load_dwordx4 v[82:85], v[4:5], off
	global_load_dwordx4 v[86:89], v[4:5], off offset:32
	global_load_dwordx4 v[90:93], v[4:5], off offset:64
	global_load_dwordx4 v[94:97], v[4:5], off offset:96
	global_load_dwordx4 v[98:101], v[4:5], off offset:128
	global_load_dwordx4 v[102:105], v[4:5], off offset:160
	global_load_dwordx4 v[106:109], v[4:5], off offset:192
	global_load_dwordx4 v[110:113], v[4:5], off offset:224
	s_lshl_b64 s[2:3], s[2:3], 16
	v_lshl_add_u64 v[182:183], v[226:227], 0, s[2:3]
	v_mov_b32_e32 v50, v215
	v_mov_b32_e32 v51, v215
	v_lshlrev_b64 v[232:233], 9, v[2:3]
	s_add_u32 s2, s9, s2
	v_mov_b32_e32 v52, v215
	v_mov_b32_e32 v53, v215
	v_mov_b32_e32 v54, v215
	v_mov_b32_e32 v55, v215
	v_mov_b32_e32 v56, v215
	v_mov_b32_e32 v57, v215
	v_mov_b32_e32 v58, v215
	v_mov_b32_e32 v59, v215
	v_mov_b32_e32 v60, v215
	v_mov_b32_e32 v61, v215
	v_mov_b32_e32 v62, v215
	v_mov_b32_e32 v63, v215
	v_mov_b32_e32 v64, v215
	v_mov_b32_e32 v65, v215
	v_mov_b64_e32 v[34:35], v[50:51]
	v_mov_b64_e32 v[18:19], v[50:51]
	v_mov_b64_e32 v[2:3], v[50:51]
	s_mov_b32 s11, 0
	s_addc_u32 s3, s10, s3
	v_mov_b32_e32 v231, 0
	v_mov_b32_e32 v248, 0xff800000
	v_mov_b64_e32 v[36:37], v[52:53]
	v_mov_b64_e32 v[38:39], v[54:55]
	v_mov_b64_e32 v[40:41], v[56:57]
	v_mov_b64_e32 v[42:43], v[58:59]
	v_mov_b64_e32 v[44:45], v[60:61]
	v_mov_b64_e32 v[46:47], v[62:63]
	v_mov_b64_e32 v[48:49], v[64:65]
	v_mov_b64_e32 v[20:21], v[52:53]
	v_mov_b64_e32 v[22:23], v[54:55]
	v_mov_b64_e32 v[24:25], v[56:57]
	v_mov_b64_e32 v[26:27], v[58:59]
	v_mov_b64_e32 v[28:29], v[60:61]
	v_mov_b64_e32 v[30:31], v[62:63]
	v_mov_b64_e32 v[32:33], v[64:65]
	v_mov_b64_e32 v[4:5], v[52:53]
	v_mov_b64_e32 v[6:7], v[54:55]
	v_mov_b64_e32 v[8:9], v[56:57]
	v_mov_b64_e32 v[10:11], v[58:59]
	v_mov_b64_e32 v[12:13], v[60:61]
	v_mov_b64_e32 v[14:15], v[62:63]
	v_mov_b64_e32 v[16:17], v[64:65]
	s_and_b32 s6, s8, 7
	s_lshl_b32 s6, s6, 13
	s_mov_b32 s7, 0
	v_lshl_add_u64 v[182:183], s[6:7], 0, v[182:183]
	global_load_dwordx4 v[114:117], v[182:183], off
	global_load_dwordx4 v[118:121], v[182:183], off offset:1024
	global_load_dwordx4 v[122:125], v[182:183], off offset:2048
	global_load_dwordx4 v[126:129], v[182:183], off offset:3072
	v_add_co_u32_e32 v184, vcc, 0x1000, v182
	s_nop 1
	v_addc_co_u32_e32 v185, vcc, 0, v183, vcc
	global_load_dwordx4 v[130:133], v[184:185], off
	global_load_dwordx4 v[134:137], v[184:185], off offset:1024
	global_load_dwordx4 v[138:141], v[184:185], off offset:2048
	global_load_dwordx4 v[142:145], v[184:185], off offset:3072
	v_lshl_add_u64 v[186:187], s[6:7], 0, v[228:229]
	v_lshl_add_u64 v[186:187], s[2:3], 0, v[186:187]
	v_add_co_u32_e32 v186, vcc, 0x22a00000, v186
	s_nop 1
	v_addc_co_u32_e32 v187, vcc, 0, v187, vcc
	v_add_co_u32_e32 v184, vcc, 0x1000, v186
	s_nop 1
	v_addc_co_u32_e32 v185, vcc, 0, v187, vcc
	global_load_dwordx4 v[146:149], v[186:187], off
	global_load_dwordx4 v[162:165], v[186:187], off offset:16
	global_load_dwordx4 v[150:153], v[186:187], off offset:2048
	global_load_dwordx4 v[166:169], v[186:187], off offset:2064
	global_load_dwordx4 v[154:157], v[184:185], off
	global_load_dwordx4 v[170:173], v[184:185], off offset:16
	global_load_dwordx4 v[158:161], v[184:185], off offset:2048
	global_load_dwordx4 v[174:177], v[184:185], off offset:2064
	v_add_u32_e32 v188, s6, v224
	v_add_u32_e32 v189, 0x10000, v188
	s_waitcnt vmcnt(0)
	ds_write_b128 v188, v[114:117]
	ds_write_b128 v188, v[118:121] offset:1024
	ds_write_b128 v188, v[122:125] offset:2048
	ds_write_b128 v188, v[126:129] offset:3072
	ds_write_b128 v188, v[130:133] offset:4096
	ds_write_b128 v188, v[134:137] offset:5120
	ds_write_b128 v188, v[138:141] offset:6144
	ds_write_b128 v188, v[142:145] offset:7168
	ds_write_b128 v189, v[146:149]
	ds_write_b128 v189, v[162:165] offset:1024
	ds_write_b128 v189, v[150:153] offset:2048
	ds_write_b128 v189, v[166:169] offset:3072
	ds_write_b128 v189, v[154:157] offset:4096
	ds_write_b128 v189, v[170:173] offset:5120
	ds_write_b128 v189, v[158:161] offset:6144
	ds_write_b128 v189, v[174:177] offset:7168
	v_mov_b32_e32 v180, v224
	v_add_u32_e32 v181, 0x10000, v224
	s_waitcnt lgkmcnt(0)
	s_barrier
	ds_read_b128 v[114:117], v180
	ds_read_b128 v[118:121], v180 offset:1024
	ds_read_b128 v[122:125], v180 offset:2048
	ds_read_b128 v[126:129], v180 offset:3072
	ds_read_b128 v[130:133], v180 offset:4096
	ds_read_b128 v[134:137], v180 offset:5120
	ds_read_b128 v[138:141], v180 offset:6144
	ds_read_b128 v[142:145], v180 offset:7168
	s_waitcnt lgkmcnt(7)
	v_mfma_f32_32x32x16_bf16 v[66:81], v[114:117], v[82:85], 0
	ds_read_b128 v[146:149], v181
	s_waitcnt lgkmcnt(7)
	v_mfma_f32_32x32x16_bf16 v[66:81], v[118:121], v[86:89], v[66:81]
	ds_read_b128 v[162:165], v181 offset:1024
	s_waitcnt lgkmcnt(7)
	v_mfma_f32_32x32x16_bf16 v[66:81], v[122:125], v[90:93], v[66:81]
	ds_read_b128 v[150:153], v181 offset:2048
	s_waitcnt lgkmcnt(7)
	v_mfma_f32_32x32x16_bf16 v[66:81], v[126:129], v[94:97], v[66:81]
	ds_read_b128 v[166:169], v181 offset:3072
	s_waitcnt lgkmcnt(7)
	v_mfma_f32_32x32x16_bf16 v[66:81], v[130:133], v[98:101], v[66:81]
	ds_read_b128 v[154:157], v181 offset:4096
	s_waitcnt lgkmcnt(7)
	v_mfma_f32_32x32x16_bf16 v[66:81], v[134:137], v[102:105], v[66:81]
	ds_read_b128 v[170:173], v181 offset:5120
	s_waitcnt lgkmcnt(7)
	v_mfma_f32_32x32x16_bf16 v[66:81], v[138:141], v[106:109], v[66:81]
	ds_read_b128 v[158:161], v181 offset:6144
	s_waitcnt lgkmcnt(7)
	v_mfma_f32_32x32x16_bf16 v[66:81], v[142:145], v[110:113], v[66:81]
	ds_read_b128 v[174:177], v181 offset:7168
	v_add_u32_e32 v180, 0x2000, v180
	s_waitcnt lgkmcnt(0)
	ds_read_b128 v[114:117], v180
	ds_read_b128 v[118:121], v180 offset:1024
	ds_read_b128 v[122:125], v180 offset:2048
	ds_read_b128 v[126:129], v180 offset:3072
	ds_read_b128 v[130:133], v180 offset:4096
	ds_read_b128 v[134:137], v180 offset:5120
	ds_read_b128 v[138:141], v180 offset:6144
	ds_read_b128 v[142:145], v180 offset:7168
	s_nop 11
.Lxa_tile:
	v_max3_f32 v212, v66, v67, v68
	v_max3_f32 v213, v69, v70, v71
	v_max3_f32 v220, v72, v73, v74
	v_max3_f32 v221, v75, v76, v77
	v_max3_f32 v238, v78, v79, v80
	v_max3_f32 v212, v212, v213, v220
	v_max3_f32 v221, v221, v238, v81
	v_max_f32_e32 v212, v212, v221
	ds_bpermute_b32 v213, v247, v212
	s_waitcnt lgkmcnt(0)
	v_mfma_f32_32x32x16_bf16 v[190:205], v[114:117], v[82:85], 0
	v_mfma_f32_32x32x16_bf16 v[190:205], v[118:121], v[86:89], v[190:205]
	v_med3_f32 v212, v212, v213, s89
	v_mul_f32_e32 v212, 0x3e0293ee, v212
	v_max_f32_e32 v213, v248, v248
	v_max_f32_e32 v220, v213, v212
	v_fma_f32 v66, v66, s67, -v220
	v_fma_f32 v67, v67, s67, -v220
	v_fma_f32 v68, v68, s67, -v220
	v_fma_f32 v69, v69, s67, -v220
	v_mfma_f32_32x32x16_bf16 v[190:205], v[122:125], v[90:93], v[190:205]
	v_fma_f32 v70, v70, s67, -v220
	v_fma_f32 v71, v71, s67, -v220
	v_fma_f32 v72, v72, s67, -v220
	v_fma_f32 v73, v73, s67, -v220
	v_mfma_f32_32x32x16_bf16 v[190:205], v[126:129], v[94:97], v[190:205]
	v_fma_f32 v74, v74, s67, -v220
	v_fma_f32 v75, v75, s67, -v220
	v_fma_f32 v76, v76, s67, -v220
	v_fma_f32 v77, v77, s67, -v220
	v_mfma_f32_32x32x16_bf16 v[190:205], v[130:133], v[98:101], v[190:205]
	v_fma_f32 v78, v78, s67, -v220
	v_fma_f32 v79, v79, s67, -v220
	v_fma_f32 v80, v80, s67, -v220
	v_fma_f32 v81, v81, s67, -v220
	v_mfma_f32_32x32x16_bf16 v[190:205], v[134:137], v[102:105], v[190:205]
	v_exp_f32_e32 v66, v66
	v_exp_f32_e32 v67, v67
	v_add_f32_e32 v221, 0, v66
	v_exp_f32_e32 v68, v68
	v_add_f32_e32 v221, v67, v221
	v_exp_f32_e32 v69, v69
	v_add_f32_e32 v221, v68, v221
	v_mfma_f32_32x32x16_bf16 v[190:205], v[138:141], v[106:109], v[190:205]
	v_exp_f32_e32 v70, v70
	v_add_f32_e32 v221, v69, v221
	v_exp_f32_e32 v71, v71
	v_add_f32_e32 v221, v70, v221
	v_exp_f32_e32 v72, v72
	v_add_f32_e32 v221, v71, v221
	v_exp_f32_e32 v73, v73
	v_add_f32_e32 v221, v72, v221
	v_mfma_f32_32x32x16_bf16 v[190:205], v[142:145], v[110:113], v[190:205]
	v_add_u32_e32 v180, 0x2000, v180
	ds_read_b128 v[114:117], v180
	ds_read_b128 v[118:121], v180 offset:1024
	ds_read_b128 v[122:125], v180 offset:2048
	ds_read_b128 v[126:129], v180 offset:3072
	ds_read_b128 v[130:133], v180 offset:4096
	ds_read_b128 v[134:137], v180 offset:5120
	ds_read_b128 v[138:141], v180 offset:6144
	ds_read_b128 v[142:145], v180 offset:7168
	v_exp_f32_e32 v74, v74
	v_add_f32_e32 v221, v73, v221
	v_exp_f32_e32 v75, v75
	v_add_f32_e32 v221, v74, v221
	v_exp_f32_e32 v76, v76
	v_add_f32_e32 v221, v75, v221
	v_exp_f32_e32 v77, v77
	v_add_f32_e32 v221, v76, v221
	v_exp_f32_e32 v78, v78
	v_add_f32_e32 v221, v77, v221
	v_exp_f32_e32 v79, v79
	v_add_f32_e32 v221, v78, v221
	v_exp_f32_e32 v80, v80
	v_add_f32_e32 v221, v79, v221
	v_exp_f32_e32 v81, v81
	v_add_f32_e32 v221, v80, v221
	v_sub_f32_e32 v213, v248, v220
	v_add_f32_e32 v221, v81, v221
	v_exp_f32_e32 v236, v213
	v_mov_b32_e32 v248, v220
	ds_bpermute_b32 v238, v247, v221
	v_cmp_neq_f32_e32 vcc, 1.0, v236
	s_cbranch_vccz .Lxa_noresc0
	v_pk_mul_f32 v[64:65], v[64:65], v[236:237] op_sel_hi:[1,0]
	v_pk_mul_f32 v[62:63], v[62:63], v[236:237] op_sel_hi:[1,0]
	v_pk_mul_f32 v[60:61], v[60:61], v[236:237] op_sel_hi:[1,0]
	v_pk_mul_f32 v[58:59], v[58:59], v[236:237] op_sel_hi:[1,0]
	v_pk_mul_f32 v[56:57], v[56:57], v[236:237] op_sel_hi:[1,0]
	v_pk_mul_f32 v[54:55], v[54:55], v[236:237] op_sel_hi:[1,0]
	v_pk_mul_f32 v[52:53], v[52:53], v[236:237] op_sel_hi:[1,0]
	v_pk_mul_f32 v[50:51], v[50:51], v[236:237] op_sel_hi:[1,0]
	v_pk_mul_f32 v[48:49], v[48:49], v[236:237] op_sel_hi:[1,0]
	v_pk_mul_f32 v[46:47], v[46:47], v[236:237] op_sel_hi:[1,0]
	v_pk_mul_f32 v[44:45], v[44:45], v[236:237] op_sel_hi:[1,0]
	v_pk_mul_f32 v[42:43], v[42:43], v[236:237] op_sel_hi:[1,0]
	v_pk_mul_f32 v[40:41], v[40:41], v[236:237] op_sel_hi:[1,0]
	v_pk_mul_f32 v[38:39], v[38:39], v[236:237] op_sel_hi:[1,0]
	v_pk_mul_f32 v[36:37], v[36:37], v[236:237] op_sel_hi:[1,0]
	v_pk_mul_f32 v[34:35], v[34:35], v[236:237] op_sel_hi:[1,0]
	v_pk_mul_f32 v[32:33], v[32:33], v[236:237] op_sel_hi:[1,0]
	v_pk_mul_f32 v[30:31], v[30:31], v[236:237] op_sel_hi:[1,0]
	v_pk_mul_f32 v[28:29], v[28:29], v[236:237] op_sel_hi:[1,0]
	v_pk_mul_f32 v[26:27], v[26:27], v[236:237] op_sel_hi:[1,0]
	v_pk_mul_f32 v[24:25], v[24:25], v[236:237] op_sel_hi:[1,0]
	v_pk_mul_f32 v[22:23], v[22:23], v[236:237] op_sel_hi:[1,0]
	v_pk_mul_f32 v[20:21], v[20:21], v[236:237] op_sel_hi:[1,0]
	v_pk_mul_f32 v[18:19], v[18:19], v[236:237] op_sel_hi:[1,0]
	v_pk_mul_f32 v[16:17], v[16:17], v[236:237] op_sel_hi:[1,0]
	v_pk_mul_f32 v[14:15], v[14:15], v[236:237] op_sel_hi:[1,0]
	v_pk_mul_f32 v[12:13], v[12:13], v[236:237] op_sel_hi:[1,0]
	v_pk_mul_f32 v[10:11], v[10:11], v[236:237] op_sel_hi:[1,0]
	v_pk_mul_f32 v[8:9], v[8:9], v[236:237] op_sel_hi:[1,0]
	v_pk_mul_f32 v[6:7], v[6:7], v[236:237] op_sel_hi:[1,0]
	v_pk_mul_f32 v[4:5], v[4:5], v[236:237] op_sel_hi:[1,0]
	v_pk_mul_f32 v[2:3], v[2:3], v[236:237] op_sel_hi:[1,0]
.Lxa_noresc0:
	s_waitcnt lgkmcnt(0)
	v_add_f32_e32 v221, v221, v238
	v_fmac_f32_e32 v221, v231, v236
	s_nop 0
	v_mov_b32_e32 v231, v221
	v_cvt_pk_bf16_f32 v66, v66, v67
	v_cvt_pk_bf16_f32 v67, v68, v69
	v_cvt_pk_bf16_f32 v68, v70, v71
	v_cvt_pk_bf16_f32 v69, v72, v73
	v_cvt_pk_bf16_f32 v70, v74, v75
	v_cvt_pk_bf16_f32 v71, v76, v77
	v_cvt_pk_bf16_f32 v72, v78, v79
	v_cvt_pk_bf16_f32 v73, v80, v81
	s_nop 1
	v_mfma_f32_32x32x16_bf16 v[50:65], v[146:149], v[66:69], v[50:65]
	v_mfma_f32_32x32x16_bf16 v[34:49], v[150:153], v[66:69], v[34:49]
	v_mfma_f32_32x32x16_bf16 v[18:33], v[154:157], v[66:69], v[18:33]
	v_mfma_f32_32x32x16_bf16 v[2:17], v[158:161], v[66:69], v[2:17]
	v_mfma_f32_32x32x16_bf16 v[50:65], v[162:165], v[70:73], v[50:65]
	v_mfma_f32_32x32x16_bf16 v[34:49], v[166:169], v[70:73], v[34:49]
	v_mfma_f32_32x32x16_bf16 v[18:33], v[170:173], v[70:73], v[18:33]
	v_mfma_f32_32x32x16_bf16 v[2:17], v[174:177], v[70:73], v[2:17]
	v_add_u32_e32 v181, 0x2000, v181
	ds_read_b128 v[146:149], v181
	ds_read_b128 v[162:165], v181 offset:1024
	ds_read_b128 v[150:153], v181 offset:2048
	ds_read_b128 v[166:169], v181 offset:3072
	ds_read_b128 v[154:157], v181 offset:4096
	ds_read_b128 v[170:173], v181 offset:5120
	ds_read_b128 v[158:161], v181 offset:6144
	ds_read_b128 v[174:177], v181 offset:7168
	v_max3_f32 v212, v190, v191, v192
	v_max3_f32 v213, v193, v194, v195
	v_max3_f32 v220, v196, v197, v198
	v_max3_f32 v221, v199, v200, v201
	v_max3_f32 v238, v202, v203, v204
	v_max3_f32 v212, v212, v213, v220
	v_max3_f32 v221, v221, v238, v205
	v_max_f32_e32 v212, v212, v221
	ds_bpermute_b32 v213, v247, v212
	s_waitcnt lgkmcnt(0)
	v_mfma_f32_32x32x16_bf16 v[66:81], v[114:117], v[82:85], 0
	v_mfma_f32_32x32x16_bf16 v[66:81], v[118:121], v[86:89], v[66:81]
	v_med3_f32 v212, v212, v213, s89
	v_mul_f32_e32 v212, 0x3e0293ee, v212
	v_max_f32_e32 v213, v248, v248
	v_max_f32_e32 v220, v213, v212
	v_fma_f32 v190, v190, s67, -v220
	v_fma_f32 v191, v191, s67, -v220
	v_fma_f32 v192, v192, s67, -v220
	v_fma_f32 v193, v193, s67, -v220
	v_mfma_f32_32x32x16_bf16 v[66:81], v[122:125], v[90:93], v[66:81]
	v_fma_f32 v194, v194, s67, -v220
	v_fma_f32 v195, v195, s67, -v220
	v_fma_f32 v196, v196, s67, -v220
	v_fma_f32 v197, v197, s67, -v220
	v_mfma_f32_32x32x16_bf16 v[66:81], v[126:129], v[94:97], v[66:81]
	v_fma_f32 v198, v198, s67, -v220
	v_fma_f32 v199, v199, s67, -v220
	v_fma_f32 v200, v200, s67, -v220
	v_fma_f32 v201, v201, s67, -v220
	v_mfma_f32_32x32x16_bf16 v[66:81], v[130:133], v[98:101], v[66:81]
	v_fma_f32 v202, v202, s67, -v220
	v_fma_f32 v203, v203, s67, -v220
	v_fma_f32 v204, v204, s67, -v220
	v_fma_f32 v205, v205, s67, -v220
	v_mfma_f32_32x32x16_bf16 v[66:81], v[134:137], v[102:105], v[66:81]
	v_exp_f32_e32 v190, v190
	v_exp_f32_e32 v191, v191
	v_add_f32_e32 v221, 0, v190
	v_exp_f32_e32 v192, v192
	v_add_f32_e32 v221, v191, v221
	v_exp_f32_e32 v193, v193
	v_add_f32_e32 v221, v192, v221
	v_mfma_f32_32x32x16_bf16 v[66:81], v[138:141], v[106:109], v[66:81]
	v_exp_f32_e32 v194, v194
	v_add_f32_e32 v221, v193, v221
	v_exp_f32_e32 v195, v195
	v_add_f32_e32 v221, v194, v221
	v_exp_f32_e32 v196, v196
	v_add_f32_e32 v221, v195, v221
	v_exp_f32_e32 v197, v197
	v_add_f32_e32 v221, v196, v221
	v_mfma_f32_32x32x16_bf16 v[66:81], v[142:145], v[110:113], v[66:81]
	v_add_u32_e32 v180, 0x2000, v180
	ds_read_b128 v[114:117], v180
	ds_read_b128 v[118:121], v180 offset:1024
	ds_read_b128 v[122:125], v180 offset:2048
	ds_read_b128 v[126:129], v180 offset:3072
	ds_read_b128 v[130:133], v180 offset:4096
	ds_read_b128 v[134:137], v180 offset:5120
	ds_read_b128 v[138:141], v180 offset:6144
	ds_read_b128 v[142:145], v180 offset:7168
	v_exp_f32_e32 v198, v198
	v_add_f32_e32 v221, v197, v221
	v_exp_f32_e32 v199, v199
	v_add_f32_e32 v221, v198, v221
	v_exp_f32_e32 v200, v200
	v_add_f32_e32 v221, v199, v221
	v_exp_f32_e32 v201, v201
	v_add_f32_e32 v221, v200, v221
	v_exp_f32_e32 v202, v202
	v_add_f32_e32 v221, v201, v221
	v_exp_f32_e32 v203, v203
	v_add_f32_e32 v221, v202, v221
	v_exp_f32_e32 v204, v204
	v_add_f32_e32 v221, v203, v221
	v_exp_f32_e32 v205, v205
	v_add_f32_e32 v221, v204, v221
	v_sub_f32_e32 v213, v248, v220
	v_add_f32_e32 v221, v205, v221
	v_exp_f32_e32 v236, v213
	v_mov_b32_e32 v248, v220
	ds_bpermute_b32 v238, v247, v221
	v_cmp_neq_f32_e32 vcc, 1.0, v236
	s_cbranch_vccz .Lxa_noresc1
	v_pk_mul_f32 v[64:65], v[64:65], v[236:237] op_sel_hi:[1,0]
	v_pk_mul_f32 v[62:63], v[62:63], v[236:237] op_sel_hi:[1,0]
	v_pk_mul_f32 v[60:61], v[60:61], v[236:237] op_sel_hi:[1,0]
	v_pk_mul_f32 v[58:59], v[58:59], v[236:237] op_sel_hi:[1,0]
	v_pk_mul_f32 v[56:57], v[56:57], v[236:237] op_sel_hi:[1,0]
	v_pk_mul_f32 v[54:55], v[54:55], v[236:237] op_sel_hi:[1,0]
	v_pk_mul_f32 v[52:53], v[52:53], v[236:237] op_sel_hi:[1,0]
	v_pk_mul_f32 v[50:51], v[50:51], v[236:237] op_sel_hi:[1,0]
	v_pk_mul_f32 v[48:49], v[48:49], v[236:237] op_sel_hi:[1,0]
	v_pk_mul_f32 v[46:47], v[46:47], v[236:237] op_sel_hi:[1,0]
	v_pk_mul_f32 v[44:45], v[44:45], v[236:237] op_sel_hi:[1,0]
	v_pk_mul_f32 v[42:43], v[42:43], v[236:237] op_sel_hi:[1,0]
	v_pk_mul_f32 v[40:41], v[40:41], v[236:237] op_sel_hi:[1,0]
	v_pk_mul_f32 v[38:39], v[38:39], v[236:237] op_sel_hi:[1,0]
	v_pk_mul_f32 v[36:37], v[36:37], v[236:237] op_sel_hi:[1,0]
	v_pk_mul_f32 v[34:35], v[34:35], v[236:237] op_sel_hi:[1,0]
	v_pk_mul_f32 v[32:33], v[32:33], v[236:237] op_sel_hi:[1,0]
	v_pk_mul_f32 v[30:31], v[30:31], v[236:237] op_sel_hi:[1,0]
	v_pk_mul_f32 v[28:29], v[28:29], v[236:237] op_sel_hi:[1,0]
	v_pk_mul_f32 v[26:27], v[26:27], v[236:237] op_sel_hi:[1,0]
	v_pk_mul_f32 v[24:25], v[24:25], v[236:237] op_sel_hi:[1,0]
	v_pk_mul_f32 v[22:23], v[22:23], v[236:237] op_sel_hi:[1,0]
	v_pk_mul_f32 v[20:21], v[20:21], v[236:237] op_sel_hi:[1,0]
	v_pk_mul_f32 v[18:19], v[18:19], v[236:237] op_sel_hi:[1,0]
	v_pk_mul_f32 v[16:17], v[16:17], v[236:237] op_sel_hi:[1,0]
	v_pk_mul_f32 v[14:15], v[14:15], v[236:237] op_sel_hi:[1,0]
	v_pk_mul_f32 v[12:13], v[12:13], v[236:237] op_sel_hi:[1,0]
	v_pk_mul_f32 v[10:11], v[10:11], v[236:237] op_sel_hi:[1,0]
	v_pk_mul_f32 v[8:9], v[8:9], v[236:237] op_sel_hi:[1,0]
	v_pk_mul_f32 v[6:7], v[6:7], v[236:237] op_sel_hi:[1,0]
	v_pk_mul_f32 v[4:5], v[4:5], v[236:237] op_sel_hi:[1,0]
	v_pk_mul_f32 v[2:3], v[2:3], v[236:237] op_sel_hi:[1,0]
; __device__ __forceinline__ void xattn_phase(const bf16* QXB, const bf16* MKF, const bf16* MVF, bf16* OXB, int G, int tid) {
;     ...
;         bf16x8 kfa[8], kfb[8];
; #pragma unroll
;         for (int ks = 0; ks < 8; ++ks) kfa[ks] = *(const bf16x8*)(kp + ks * 512);
; #pragma unroll 1
;         for (int kt = 0; kt < 8; kt += 2) { XA_TILE(kt, kfa, kfb, true) XA_TILE(kt + 1, kfb, kfa, kt + 2 < 8) }
.Lxa_noresc1:
	s_waitcnt lgkmcnt(0)
	v_add_f32_e32 v221, v221, v238
	v_fmac_f32_e32 v221, v231, v236
	s_nop 0
	v_mov_b32_e32 v231, v221
	v_cvt_pk_bf16_f32 v190, v190, v191
	v_cvt_pk_bf16_f32 v191, v192, v193
	v_cvt_pk_bf16_f32 v192, v194, v195
	v_cvt_pk_bf16_f32 v193, v196, v197
	v_cvt_pk_bf16_f32 v194, v198, v199
	v_cvt_pk_bf16_f32 v195, v200, v201
	v_cvt_pk_bf16_f32 v196, v202, v203
	v_cvt_pk_bf16_f32 v197, v204, v205
	s_nop 1
	v_mfma_f32_32x32x16_bf16 v[50:65], v[146:149], v[190:193], v[50:65]
	v_mfma_f32_32x32x16_bf16 v[34:49], v[150:153], v[190:193], v[34:49]
	v_mfma_f32_32x32x16_bf16 v[18:33], v[154:157], v[190:193], v[18:33]
	v_mfma_f32_32x32x16_bf16 v[2:17], v[158:161], v[190:193], v[2:17]
	v_mfma_f32_32x32x16_bf16 v[50:65], v[162:165], v[194:197], v[50:65]
	v_mfma_f32_32x32x16_bf16 v[34:49], v[166:169], v[194:197], v[34:49]
	v_mfma_f32_32x32x16_bf16 v[18:33], v[170:173], v[194:197], v[18:33]
	v_mfma_f32_32x32x16_bf16 v[2:17], v[174:177], v[194:197], v[2:17]
	v_add_u32_e32 v181, 0x2000, v181
	ds_read_b128 v[146:149], v181
	ds_read_b128 v[162:165], v181 offset:1024
	ds_read_b128 v[150:153], v181 offset:2048
	ds_read_b128 v[166:169], v181 offset:3072
	ds_read_b128 v[154:157], v181 offset:4096
	ds_read_b128 v[170:173], v181 offset:5120
	ds_read_b128 v[158:161], v181 offset:6144
	ds_read_b128 v[174:177], v181 offset:7168
	s_add_i32 s11, s11, 2
	s_cmp_lt_u32 s11, 8
	s_cbranch_scc1 .Lxa_tile
	s_waitcnt lgkmcnt(0)
	s_nop 15
	s_branch .LBB0_1510
